# SWA attention unit prologue de-serialised: bias-table loads issued with the K/V LDS-DMAs and Q loads, LDS writes after one drain (1 memory round trip instead of 3 per unit); bit-exact, same numerics
# speedup vs baseline: 1.0083x; 1.0005x over previous
	.amdhsa_kernel _Z10fwd_kernel4Args
		.amdhsa_group_segment_fixed_size 0
		.amdhsa_private_segment_fixed_size 0
		.amdhsa_kernarg_size 536
		.amdhsa_user_sgpr_count 2
		.amdhsa_user_sgpr_dispatch_ptr 0
		.amdhsa_user_sgpr_queue_ptr 0
		.amdhsa_user_sgpr_kernarg_segment_ptr 1
		.amdhsa_user_sgpr_dispatch_id 0
		.amdhsa_user_sgpr_kernarg_preload_length 0
		.amdhsa_user_sgpr_kernarg_preload_offset 0
		.amdhsa_user_sgpr_private_segment_size 0
		.amdhsa_uses_dynamic_stack 0
		.amdhsa_enable_private_segment 0
		.amdhsa_system_sgpr_workgroup_id_x 1
		.amdhsa_system_sgpr_workgroup_id_y 0
		.amdhsa_system_sgpr_workgroup_id_z 0
		.amdhsa_system_sgpr_workgroup_info 0
		.amdhsa_system_vgpr_workitem_id 0
		.amdhsa_next_free_vgpr 254
		.amdhsa_next_free_sgpr 98
		.amdhsa_accum_offset 256
		.amdhsa_reserve_vcc 1
		.amdhsa_float_round_mode_32 0
		.amdhsa_float_round_mode_16_64 0
		.amdhsa_float_denorm_mode_32 3
		.amdhsa_float_denorm_mode_16_64 3
		.amdhsa_dx10_clamp 1
		.amdhsa_ieee_mode 1
		.amdhsa_fp16_overflow 0
		.amdhsa_tg_split 0
		.amdhsa_exception_fp_ieee_invalid_op 0
		.amdhsa_exception_fp_denorm_src 0
		.amdhsa_exception_fp_ieee_div_zero 0
		.amdhsa_exception_fp_ieee_overflow 0
		.amdhsa_exception_fp_ieee_underflow 0
		.amdhsa_exception_fp_ieee_inexact 0
		.amdhsa_exception_int_div_zero 0
	.end_amdhsa_kernel

amdhsa.kernels:
  - .agpr_count:     0
    .args:
      - .offset:         0
        .size:           280
        .value_kind:     by_value
      - .offset:         280
        .size:           4
        .value_kind:     hidden_block_count_x
      - .offset:         284
        .size:           4
        .value_kind:     hidden_block_count_y
      - .offset:         288
        .size:           4
        .value_kind:     hidden_block_count_z
      - .offset:         292
        .size:           2
        .value_kind:     hidden_group_size_x
      - .offset:         294
        .size:           2
        .value_kind:     hidden_group_size_y
      - .offset:         296
        .size:           2
        .value_kind:     hidden_group_size_z
      - .offset:         298
        .size:           2
        .value_kind:     hidden_remainder_x
      - .offset:         300
        .size:           2
        .value_kind:     hidden_remainder_y
      - .offset:         302
        .size:           2
        .value_kind:     hidden_remainder_z
      - .offset:         320
        .size:           8
        .value_kind:     hidden_global_offset_x
      - .offset:         328
        .size:           8
        .value_kind:     hidden_global_offset_y
      - .offset:         336
        .size:           8
        .value_kind:     hidden_global_offset_z
      - .offset:         344
        .size:           2
        .value_kind:     hidden_grid_dims
      - .offset:         400
        .size:           4
        .value_kind:     hidden_dynamic_lds_size
    .group_segment_fixed_size: 0
    .kernarg_segment_align: 8
    .kernarg_segment_size: 536
    .language:       OpenCL C
    .language_version:
      - 2
      - 0
    .max_flat_workgroup_size: 512
    .name:           _Z10fwd_kernel4Args
    .private_segment_fixed_size: 0
    .sgpr_count:     104
    .sgpr_spill_count: 58
    .symbol:         _Z10fwd_kernel4Args.kd
    .uniform_work_group_size: 1
    .uses_dynamic_stack: false
    .vgpr_count:     254
    .vgpr_spill_count: 0
    .wavefront_size: 64
